# diff loop: the four QK fragment reads of a 64-key step issued together into their own registers, counted waits (on top of the rowpass0 pointer version)
# speedup vs baseline: 1.0092x; 1.0025x over previous
.LBB0_581:
	v_add_u32_e32 v161, s22, v218
	v_add_u32_e32 v160, s22, v217
	ds_read_b128 v[112:115], v161
	v_add_u32_e32 v222, s22, v216
	ds_read_b128 v[116:119], v160
	v_add_u32_e32 v221, s22, v215
	ds_read_b128 v[120:123], v222
	ds_read_b128 v[124:127], v221
	s_or_b32 s0, s23, s18
	s_cmp_eq_u32 s0, 0
	s_cselect_b64 s[14:15], -1, 0
	s_and_b64 s[2:3], exec, s[14:15]
	s_waitcnt lgkmcnt(3)
	v_mfma_f32_32x32x16_bf16 v[96:111], v[112:115], v[152:155], v[64:79]
	s_waitcnt lgkmcnt(2)
	v_mfma_f32_32x32x16_bf16 v[96:111], v[116:119], v[144:147], v[96:111]
	s_waitcnt lgkmcnt(1)
	v_mfma_f32_32x32x16_bf16 v[128:143], v[120:123], v[148:151], v[80:95]
	s_waitcnt lgkmcnt(0)
	v_mfma_f32_32x32x16_bf16 v[128:143], v[124:127], v[156:159], v[128:143]
	s_nop 7
	v_max3_f32 v112, v96, v97, v98
	v_max_f32_e32 v112, v112, v99
	v_max3_f32 v112, v112, v100, v101
	v_max3_f32 v112, v112, v102, v103
	v_max3_f32 v112, v112, v104, v105
	v_max3_f32 v112, v112, v106, v107
	v_max3_f32 v112, v112, v108, v109
	v_max3_f32 v112, v112, v110, v111
	v_cmp_nge_f32_e32 vcc, s85, v112
	s_or_b64 vcc, vcc, s[2:3]
	s_cbranch_vccz .LBB0_587
	v_and_b32_e32 v65, 64, v196
	v_xor_b32_e32 v64, 32, v196
	v_add_u32_e32 v65, 64, v65
	v_cmp_lt_i32_e32 vcc, v64, v65
	v_max_f32_e32 v65, v112, v112
	s_nop 0
	v_cndmask_b32_e32 v64, v196, v64, vcc
	v_lshlrev_b32_e32 v64, 2, v64
	ds_bpermute_b32 v64, v64, v112
	s_and_b64 vcc, exec, s[2:3]
	s_waitcnt lgkmcnt(0)
	v_max_f32_e32 v64, v64, v64
	v_max_f32_e32 v64, v65, v64
	v_max_f32_e32 v65, 0, v64
	s_cbranch_vccnz .LBB0_586
	v_exp_f32_e64 v66, -v65
	s_nop 0
	v_mul_f32_e32 v220, v220, v66
	v_pk_mul_f32 v[14:15], v[14:15], v[66:67] op_sel_hi:[1,0]
	v_pk_mul_f32 v[12:13], v[12:13], v[66:67] op_sel_hi:[1,0]
	v_pk_mul_f32 v[10:11], v[10:11], v[66:67] op_sel_hi:[1,0]
	v_pk_mul_f32 v[8:9], v[8:9], v[66:67] op_sel_hi:[1,0]
	v_pk_mul_f32 v[6:7], v[6:7], v[66:67] op_sel_hi:[1,0]
	v_pk_mul_f32 v[4:5], v[4:5], v[66:67] op_sel_hi:[1,0]
	v_pk_mul_f32 v[2:3], v[2:3], v[66:67] op_sel_hi:[1,0]
	v_pk_mul_f32 v[0:1], v[0:1], v[66:67] op_sel_hi:[1,0]
	v_pk_mul_f32 v[46:47], v[46:47], v[66:67] op_sel_hi:[1,0]
	v_pk_mul_f32 v[44:45], v[44:45], v[66:67] op_sel_hi:[1,0]
	v_pk_mul_f32 v[42:43], v[42:43], v[66:67] op_sel_hi:[1,0]
	v_pk_mul_f32 v[40:41], v[40:41], v[66:67] op_sel_hi:[1,0]
	v_pk_mul_f32 v[38:39], v[38:39], v[66:67] op_sel_hi:[1,0]
	v_pk_mul_f32 v[36:37], v[36:37], v[66:67] op_sel_hi:[1,0]
	v_pk_mul_f32 v[34:35], v[34:35], v[66:67] op_sel_hi:[1,0]
	v_pk_mul_f32 v[32:33], v[32:33], v[66:67] op_sel_hi:[1,0]
